# v59 + L2 touches of the next attention unit's first K/V tiles in the final step
# speedup vs baseline: 1.0059x; 1.0038x over previous
.Lmy_t_q:
	s_add_i32 s52, s75, 1
	s_cmp_ge_u32 s52, 8
	s_cbranch_scc1 .Lmy_t_last
	s_and_b32 s53, s52, 1
	s_lshr_b32 s52, s52, 1
	s_sub_i32 s54, 15, s61
	s_bitcmp1_b32 s52, 0
	s_cselect_b32 s54, s54, s61
	s_and_b32 s55, s52, 2
	s_lshl_b32 s55, s55, 3
	s_add_i32 s54, s54, s55
	s_lshl_b32 s54, s54, 8
	s_lshr_b32 s55, s60, 3
	s_lshl_b32 s55, s55, 13
	s_add_i32 s54, s54, s55
	s_lshr_b32 s55, s85, 1
	s_add_i32 s54, s54, s55
	s_lshl_b32 s56, s54, 11
	s_lshl_b32 s55, s57, 1
	s_add_i32 s55, s55, s53
	s_lshl_b32 s55, s55, 7
	s_add_u32 s56, s56, s55
	s_add_u32 s56, s56, 0x2800000
	s_add_u32 s58, s22, s56
	s_addc_u32 s59, s23, 0
	v_lshlrev_b32_e32 v254, 11, v212
	v_lshl_or_b32 v254, v213, 6, v254
	global_load_dword v255, v254, s[58:59]
	s_lshr_b32 s54, s60, 3
	s_lshl_b32 s54, s54, 24
	s_lshl_b32 s55, s57, 1
	s_add_i32 s55, s55, s53
	s_lshl_b32 s55, s55, 7
	s_add_u32 s55, s55, s54
	s_add_u32 s55, s55, 0x6800000
	s_add_u32 s58, s22, s55
	s_addc_u32 s59, s23, 0
	v_min_u32_e32 v254, 0xbf, v234
	v_lshlrev_b32_e32 v254, 11, v254
	global_load_dword v255, v254, s[58:59]
	s_lshl_b32 s55, s57, 8
	s_add_u32 s55, s55, s54
	s_add_u32 s55, s55, 0xa800000
	s_add_u32 s58, s22, s55
	s_addc_u32 s59, s23, 0
	v_bfe_u32 v254, v234, 1, 7
	v_lshlrev_b32_e32 v254, 11, v254
	v_and_b32_e32 v213, 1, v234
	v_lshl_or_b32 v254, v213, 7, v254
	global_load_dword v255, v254, s[58:59]
